# attention loop: V LDS-DMA issues moved down into the P.V MFMA gaps (after MFMA 3 and 7); s_nop 1 keeps the MFMA->exp distance
# baseline (speedup 1.0000x reference)
.LBB0_429:
	s_mov_b32 s46, s75
	s_mov_b32 s47, s74
	s_mov_b32 s49, s51
	v_lshl_add_u32 v0, s48, 1, v218
	s_lshl_b32 s48, s76, 1
	v_add_u32_e32 v14, s48, v228
	ds_read_b128 v[2:5], v14 offset:4096
	ds_read_b128 v[6:9], v14 offset:6144
	ds_read_b64_tr_b16 v[10:11], v0
	ds_read_b64_tr_b16 v[12:13], v0 offset:512
	s_waitcnt lgkmcnt(5)
	v_mfma_f32_32x32x16_bf16 v[92:107], v[156:159], v[120:123], 0
	ds_read_b128 v[80:83], v14 offset:512
	ds_read_b128 v[156:159], v14 offset:2560
	ds_read_b64_tr_b16 v[164:165], v0 offset:4096
	ds_read_b64_tr_b16 v[166:167], v0 offset:4608
	s_waitcnt lgkmcnt(8)
	v_mfma_f32_32x32x16_bf16 v[92:107], v[160:163], v[116:119], v[92:107]
	ds_read_b128 v[160:163], v14 offset:4608
	ds_read_b128 v[168:171], v14 offset:6656
	ds_read_b64_tr_b16 v[172:173], v0 offset:1024
	ds_read_b64_tr_b16 v[174:175], v0 offset:1536
	s_waitcnt lgkmcnt(11)
	v_mfma_f32_32x32x16_bf16 v[92:107], v[2:5], v[112:115], v[92:107]
	ds_read_b64_tr_b16 v[2:3], v0 offset:5120
	ds_read_b64_tr_b16 v[4:5], v0 offset:5632
	s_waitcnt lgkmcnt(12)
	v_mfma_f32_32x32x16_bf16 v[92:107], v[6:9], v[108:111], v[92:107]
	s_add_u32 s74, s44, 0xff020000
	s_addc_u32 s75, s45, -1
	s_lshl_b32 s51, s77, 1
	s_add_i32 s51, s51, s72
	s_mov_b32 s76, m0
	s_mov_b32 m0, s51
	s_nop 0
	global_load_lds_dwordx4 v226, s[74:75]
	s_mov_b32 m0, s76
	s_add_u32 s74, s44, 0xff020080
	s_addc_u32 s75, s45, -1
	s_addk_i32 s51, 0x2000
	s_mov_b32 s76, m0
	s_mov_b32 m0, s51
	s_nop 0
	global_load_lds_dwordx4 v226, s[74:75]
	s_mov_b32 m0, s76
	v_exp_f32_e32 v14, v92
	v_exp_f32_e32 v15, v93
	v_exp_f32_e32 v124, v94
	v_exp_f32_e32 v128, v95
	s_waitcnt lgkmcnt(9)
	v_mfma_f32_32x32x16_bf16 v[80:95], v[80:83], v[120:123], 0
	ds_read_b64_tr_b16 v[6:7], v0 offset:2048
	ds_read_b64_tr_b16 v[8:9], v0 offset:2560
	v_add_f32_e32 v132, 0, v14
	v_add_f32_e32 v132, v15, v132
	v_add_f32_e32 v132, v124, v132
	v_add_f32_e32 v132, v128, v132
	v_cvt_pk_bf16_f32 v136, v14, v15
	v_cvt_pk_bf16_f32 v137, v124, v128
	v_exp_f32_e32 v14, v96
	v_exp_f32_e32 v15, v97
	v_exp_f32_e32 v124, v98
	s_waitcnt lgkmcnt(10)
	v_mfma_f32_32x32x16_bf16 v[80:95], v[156:159], v[116:119], v[80:95]
	v_exp_f32_e32 v128, v99
	ds_read_b64_tr_b16 v[96:97], v0 offset:6144
	ds_read_b64_tr_b16 v[98:99], v0 offset:6656
	v_add_f32_e32 v132, v14, v132
	v_add_f32_e32 v132, v15, v132
	v_add_f32_e32 v132, v124, v132
	v_add_f32_e32 v132, v128, v132
	v_cvt_pk_bf16_f32 v138, v14, v15
	v_cvt_pk_bf16_f32 v139, v124, v128
	v_exp_f32_e32 v14, v100
	v_exp_f32_e32 v15, v101
	v_exp_f32_e32 v124, v102
	s_waitcnt lgkmcnt(9)
	v_mfma_f32_32x32x16_bf16 v[80:95], v[160:163], v[112:115], v[80:95]
	v_exp_f32_e32 v128, v103
	ds_read_b64_tr_b16 v[100:101], v0 offset:3072
	ds_read_b64_tr_b16 v[102:103], v0 offset:3584
	v_add_f32_e32 v132, v14, v132
	v_add_f32_e32 v132, v15, v132
	v_add_f32_e32 v132, v124, v132
	v_add_f32_e32 v156, v128, v132
	v_cvt_pk_bf16_f32 v132, v14, v15
	v_cvt_pk_bf16_f32 v133, v124, v128
	v_exp_f32_e32 v14, v104
	v_exp_f32_e32 v15, v105
	v_exp_f32_e32 v124, v106
	s_waitcnt lgkmcnt(10)
	v_mfma_f32_32x32x16_bf16 v[80:95], v[168:171], v[108:111], v[80:95]
	v_exp_f32_e32 v128, v107
	ds_read_b64_tr_b16 v[104:105], v0 offset:7168
	ds_read_b64_tr_b16 v[106:107], v0 offset:7680
	v_add_f32_e32 v134, v14, v156
	v_add_f32_e32 v134, v15, v134
	v_add_f32_e32 v134, v124, v134
	v_add_f32_e32 v156, v128, v134
	v_cvt_pk_bf16_f32 v134, v14, v15
	v_cvt_pk_bf16_f32 v135, v124, v128
	s_nop 1
	v_mfma_f32_32x32x16_bf16 v[16:31], v[152:155], v[10:13], v[16:31]
	v_exp_f32_e32 v14, v80
	ds_read_b64_tr_b16 v[10:11], v0 offset:8192
	ds_read_b64_tr_b16 v[12:13], v0 offset:8704
	v_exp_f32_e32 v15, v81
	v_mov_b32_e32 v80, v14
	v_add_f32_e32 v14, v14, v156
	s_nop 0
	v_cvt_pk_bf16_f32 v128, v80, v15
	v_mfma_f32_32x32x16_bf16 v[32:47], v[152:155], v[164:167], v[32:47]
	ds_read_b64_tr_b16 v[156:157], v0 offset:12288
	ds_read_b64_tr_b16 v[158:159], v0 offset:12800
	v_add_f32_e32 v14, v15, v14
	s_waitcnt lgkmcnt(14)
	v_mfma_f32_32x32x16_bf16 v[16:31], v[148:151], v[172:175], v[16:31]
	s_add_u32 s74, s44, 0xfffe0000
	s_addc_u32 s75, s45, -1
	s_lshl_b32 s51, s47, 1
	s_add_i32 s51, s51, s73
	s_mov_b32 s76, m0
	s_mov_b32 m0, s51
	s_nop 0
	global_load_lds_dwordx4 v227, s[74:75]
	s_mov_b32 m0, s76
	v_exp_f32_e32 v15, v82
	ds_read_b64_tr_b16 v[160:161], v0 offset:9216
	ds_read_b64_tr_b16 v[162:163], v0 offset:9728
	v_add_f32_e32 v14, v15, v14
	s_waitcnt lgkmcnt(14)
	v_mfma_f32_32x32x16_bf16 v[32:47], v[148:151], v[2:5], v[32:47]
	v_exp_f32_e32 v80, v83
	ds_read_b64_tr_b16 v[2:3], v0 offset:13312
	ds_read_b64_tr_b16 v[4:5], v0 offset:13824
	v_add_f32_e32 v14, v80, v14
	v_cvt_pk_bf16_f32 v129, v15, v80
	s_waitcnt lgkmcnt(14)
	v_mfma_f32_32x32x16_bf16 v[16:31], v[144:147], v[6:9], v[16:31]
	v_exp_f32_e32 v15, v84
	ds_read_b64_tr_b16 v[6:7], v0 offset:10240
	ds_read_b64_tr_b16 v[8:9], v0 offset:10752
	v_add_f32_e32 v14, v15, v14
	s_waitcnt lgkmcnt(14)
	v_mfma_f32_32x32x16_bf16 v[32:47], v[144:147], v[96:99], v[32:47]
	v_exp_f32_e32 v84, v85
	ds_read_b64_tr_b16 v[80:81], v0 offset:14336
	ds_read_b64_tr_b16 v[82:83], v0 offset:14848
	v_add_f32_e32 v14, v84, v14
	v_cvt_pk_bf16_f32 v130, v15, v84
	s_waitcnt lgkmcnt(14)
	v_mfma_f32_32x32x16_bf16 v[16:31], v[140:143], v[100:103], v[16:31]
	s_add_u32 s74, s44, 0xfffe0080
	s_addc_u32 s75, s45, -1
	s_addk_i32 s51, 0x2000
	s_mov_b32 s76, m0
	s_mov_b32 m0, s51
	s_nop 0
	global_load_lds_dwordx4 v227, s[74:75]
	s_mov_b32 m0, s76
	v_exp_f32_e32 v15, v86
	ds_read_b64_tr_b16 v[96:97], v0 offset:11264
	ds_read_b64_tr_b16 v[98:99], v0 offset:11776
	v_add_f32_e32 v14, v15, v14
	s_waitcnt lgkmcnt(14)
	v_mfma_f32_32x32x16_bf16 v[32:47], v[140:143], v[104:107], v[32:47]
	v_exp_f32_e32 v100, v87
	ds_read_b64_tr_b16 v[84:85], v0 offset:15360
	ds_read_b64_tr_b16 v[86:87], v0 offset:15872
	v_add_f32_e32 v0, v100, v14
	v_cvt_pk_bf16_f32 v131, v15, v100
	v_exp_f32_e32 v14, v88
	v_exp_f32_e32 v15, v89
	s_waitcnt lgkmcnt(14)
	v_mfma_f32_32x32x16_bf16 v[48:63], v[152:155], v[10:13], v[48:63]
	v_lshl_add_u32 v88, s46, 1, v228
	v_mov_b32_e32 v89, v14
	v_add_f32_e32 v0, v14, v0
	s_nop 0
	v_cvt_pk_bf16_f32 v124, v89, v15
	s_waitcnt lgkmcnt(12)
	v_mfma_f32_32x32x16_bf16 v[64:79], v[152:155], v[156:159], v[64:79]
	v_add_f32_e32 v0, v15, v0
	v_exp_f32_e32 v10, v90
	s_waitcnt lgkmcnt(10)
	v_mfma_f32_32x32x16_bf16 v[48:63], v[148:151], v[160:163], v[48:63]
	v_add_f32_e32 v0, v10, v0
	v_exp_f32_e32 v11, v91
	s_waitcnt lgkmcnt(8)
	v_mfma_f32_32x32x16_bf16 v[64:79], v[148:151], v[2:5], v[64:79]
	v_add_f32_e32 v0, v11, v0
	v_cvt_pk_bf16_f32 v125, v10, v11
	v_exp_f32_e32 v10, v92
	s_waitcnt lgkmcnt(6)
	v_mfma_f32_32x32x16_bf16 v[48:63], v[144:147], v[6:9], v[48:63]
	v_add_f32_e32 v0, v10, v0
	v_exp_f32_e32 v6, v93
	s_waitcnt lgkmcnt(4)
	v_mfma_f32_32x32x16_bf16 v[64:79], v[144:147], v[80:83], v[64:79]
	ds_read_b128 v[2:5], v88
	v_add_f32_e32 v0, v6, v0
	v_cvt_pk_bf16_f32 v126, v10, v6
	v_exp_f32_e32 v10, v94
	s_waitcnt lgkmcnt(3)
	v_mfma_f32_32x32x16_bf16 v[48:63], v[140:143], v[96:99], v[48:63]
	v_add_f32_e32 v0, v10, v0
	v_exp_f32_e32 v11, v95
	s_waitcnt lgkmcnt(1)
	v_mfma_f32_32x32x16_bf16 v[64:79], v[140:143], v[84:87], v[64:79]
	ds_read_b128 v[6:9], v88 offset:2048
	v_add_f32_e32 v0, v11, v0
	v_cvt_pk_bf16_f32 v127, v10, v11
	s_add_i32 s51, s47, 0x2000
	s_cmpk_lg_i32 s47, 0x4000
	s_waitcnt vmcnt(4) lgkmcnt(0)
	s_barrier
	s_cselect_b32 s51, s51, 0
	s_add_i32 s74, s46, 0x2000
	s_cmpk_lg_i32 s46, 0x6000
	s_cselect_b32 s76, s74, 0
	v_add_f32_e32 v0, v229, v0
	v_lshl_add_u32 v14, s49, 1, v218
	ds_read_b128 v[10:13], v88 offset:4096
	ds_read_b128 v[80:83], v88 offset:6144
	ds_read_b64_tr_b16 v[156:157], v14
	ds_read_b64_tr_b16 v[158:159], v14 offset:512
	v_lshl_add_u32 v15, s76, 1, v228
	s_waitcnt lgkmcnt(5)
	v_mfma_f32_32x32x16_bf16 v[92:107], v[2:5], v[120:123], 0
	ds_read_b128 v[2:5], v88 offset:512
	ds_read_b128 v[160:163], v88 offset:2560
	ds_read_b64_tr_b16 v[164:165], v14 offset:4096
	ds_read_b64_tr_b16 v[166:167], v14 offset:4608
	s_waitcnt lgkmcnt(8)
	v_mfma_f32_32x32x16_bf16 v[92:107], v[6:9], v[116:119], v[92:107]
	ds_read_b128 v[6:9], v88 offset:4608
	ds_read_b128 v[168:171], v88 offset:6656
	ds_read_b64_tr_b16 v[172:173], v14 offset:1024
	ds_read_b64_tr_b16 v[174:175], v14 offset:1536
	s_waitcnt lgkmcnt(11)
	v_mfma_f32_32x32x16_bf16 v[92:107], v[10:13], v[112:115], v[92:107]
	ds_read_b64_tr_b16 v[10:11], v14 offset:5120
	ds_read_b64_tr_b16 v[12:13], v14 offset:5632
	s_waitcnt lgkmcnt(12)
	v_mfma_f32_32x32x16_bf16 v[92:107], v[80:83], v[108:111], v[92:107]
	s_add_u32 s74, s44, 0xff040000
	s_addc_u32 s75, s45, -1
	s_add_i32 s77, s48, s72
	s_mov_b32 s48, m0
	s_mov_b32 m0, s77
	s_nop 0
	global_load_lds_dwordx4 v226, s[74:75]
	s_mov_b32 m0, s48
	s_add_u32 s48, s44, 0xff040080
	s_addc_u32 s49, s45, -1
	s_add_i32 s74, s77, 0x2000
	s_mov_b32 s75, m0
	s_mov_b32 m0, s74
	s_nop 0
	global_load_lds_dwordx4 v226, s[48:49]
	s_mov_b32 m0, s75
	v_exp_f32_e32 v140, v92
	v_exp_f32_e32 v144, v93
	v_exp_f32_e32 v148, v94
	v_exp_f32_e32 v149, v95
	s_waitcnt lgkmcnt(9)
	v_mfma_f32_32x32x16_bf16 v[80:95], v[2:5], v[120:123], 0
	ds_read_b64_tr_b16 v[2:3], v14 offset:2048
	ds_read_b64_tr_b16 v[4:5], v14 offset:2560
	v_add_f32_e32 v152, 0, v140
	v_add_f32_e32 v152, v144, v152
	v_add_f32_e32 v152, v148, v152
	v_add_f32_e32 v176, v149, v152
	v_cvt_pk_bf16_f32 v152, v140, v144
	v_cvt_pk_bf16_f32 v153, v148, v149
	v_exp_f32_e32 v140, v96
	v_exp_f32_e32 v144, v97
	v_exp_f32_e32 v148, v98
	s_waitcnt lgkmcnt(10)
	v_mfma_f32_32x32x16_bf16 v[80:95], v[160:163], v[116:119], v[80:95]
	v_exp_f32_e32 v149, v99
	ds_read_b64_tr_b16 v[96:97], v14 offset:6144
	ds_read_b64_tr_b16 v[98:99], v14 offset:6656
	v_add_f32_e32 v154, v140, v176
	v_add_f32_e32 v154, v144, v154
	v_add_f32_e32 v154, v148, v154
	v_add_f32_e32 v160, v149, v154
	v_cvt_pk_bf16_f32 v154, v140, v144
	v_cvt_pk_bf16_f32 v155, v148, v149
	v_exp_f32_e32 v100, v100
	v_exp_f32_e32 v101, v101
	v_exp_f32_e32 v102, v102
	s_waitcnt lgkmcnt(9)
	v_mfma_f32_32x32x16_bf16 v[80:95], v[6:9], v[112:115], v[80:95]
	v_exp_f32_e32 v103, v103
	ds_read_b64_tr_b16 v[6:7], v14 offset:3072
	ds_read_b64_tr_b16 v[8:9], v14 offset:3584
	v_add_f32_e32 v140, v100, v160
	v_add_f32_e32 v140, v101, v140
	v_add_f32_e32 v140, v102, v140
	v_add_f32_e32 v140, v103, v140
	v_cvt_pk_bf16_f32 v148, v100, v101
	v_cvt_pk_bf16_f32 v149, v102, v103
	v_exp_f32_e32 v104, v104
	v_exp_f32_e32 v105, v105
	v_exp_f32_e32 v106, v106
	s_waitcnt lgkmcnt(10)
	v_mfma_f32_32x32x16_bf16 v[80:95], v[168:171], v[108:111], v[80:95]
	v_exp_f32_e32 v107, v107
	ds_read_b64_tr_b16 v[100:101], v14 offset:7168
	ds_read_b64_tr_b16 v[102:103], v14 offset:7680
	v_add_f32_e32 v140, v104, v140
	v_add_f32_e32 v140, v105, v140
	v_add_f32_e32 v140, v106, v140
	v_add_f32_e32 v140, v107, v140
	v_cvt_pk_bf16_f32 v150, v104, v105
	v_cvt_pk_bf16_f32 v151, v106, v107
	s_nop 1
	v_mfma_f32_32x32x16_bf16 v[16:31], v[136:139], v[156:159], v[16:31]
	v_exp_f32_e32 v80, v80
	ds_read_b64_tr_b16 v[104:105], v14 offset:8192
	ds_read_b64_tr_b16 v[106:107], v14 offset:8704
	v_add_f32_e32 v140, v80, v140
	v_mfma_f32_32x32x16_bf16 v[32:47], v[136:139], v[164:167], v[32:47]
	v_exp_f32_e32 v81, v81
	ds_read_b64_tr_b16 v[156:157], v14 offset:12288
	ds_read_b64_tr_b16 v[158:159], v14 offset:12800
	v_add_f32_e32 v140, v81, v140
	v_cvt_pk_bf16_f32 v144, v80, v81
	s_waitcnt lgkmcnt(14)
	v_mfma_f32_32x32x16_bf16 v[16:31], v[132:135], v[172:175], v[16:31]
	s_lshl_b32 s48, s51, 1
	s_add_i32 s42, s42, 2
	s_add_i32 s74, s48, s73
	s_mov_b32 s48, m0
	s_mov_b32 m0, s74
	s_nop 0
	global_load_lds_dwordx4 v227, s[44:45]
	s_mov_b32 m0, s48
	v_exp_f32_e32 v80, v82
	ds_read_b64_tr_b16 v[160:161], v14 offset:9216
	ds_read_b64_tr_b16 v[162:163], v14 offset:9728
	v_add_f32_e32 v81, v80, v140
	s_waitcnt lgkmcnt(14)
	v_mfma_f32_32x32x16_bf16 v[32:47], v[132:135], v[10:13], v[32:47]
	v_exp_f32_e32 v82, v83
	ds_read_b64_tr_b16 v[10:11], v14 offset:13312
	ds_read_b64_tr_b16 v[12:13], v14 offset:13824
	v_add_f32_e32 v81, v82, v81
	v_cvt_pk_bf16_f32 v145, v80, v82
	s_waitcnt lgkmcnt(14)
	v_mfma_f32_32x32x16_bf16 v[16:31], v[128:131], v[2:5], v[16:31]
	v_exp_f32_e32 v84, v84
	ds_read_b64_tr_b16 v[2:3], v14 offset:10240
	ds_read_b64_tr_b16 v[4:5], v14 offset:10752
	v_add_f32_e32 v140, v84, v81
	s_waitcnt lgkmcnt(14)
	v_mfma_f32_32x32x16_bf16 v[32:47], v[128:131], v[96:99], v[32:47]
	v_exp_f32_e32 v85, v85
	ds_read_b64_tr_b16 v[80:81], v14 offset:14336
	ds_read_b64_tr_b16 v[82:83], v14 offset:14848
	v_add_f32_e32 v96, v85, v140
	v_cvt_pk_bf16_f32 v146, v84, v85
	s_waitcnt lgkmcnt(14)
	v_mfma_f32_32x32x16_bf16 v[16:31], v[124:127], v[6:9], v[16:31]
	s_add_u32 s48, s44, 0x80
	s_addc_u32 s49, s45, 0
	s_addk_i32 s74, 0x2000
	s_mov_b32 s75, m0
	s_mov_b32 m0, s74
	s_nop 0
	global_load_lds_dwordx4 v227, s[48:49]
	s_mov_b32 m0, s75
	v_exp_f32_e32 v97, v86
	ds_read_b64_tr_b16 v[6:7], v14 offset:11264
	ds_read_b64_tr_b16 v[8:9], v14 offset:11776
	v_add_f32_e32 v96, v97, v96
	s_waitcnt lgkmcnt(14)
	v_mfma_f32_32x32x16_bf16 v[32:47], v[124:127], v[100:103], v[32:47]
	v_exp_f32_e32 v98, v87
	ds_read_b64_tr_b16 v[84:85], v14 offset:15360
	ds_read_b64_tr_b16 v[86:87], v14 offset:15872
	v_add_f32_e32 v14, v98, v96
	v_cvt_pk_bf16_f32 v147, v97, v98
	v_exp_f32_e32 v88, v88
	s_waitcnt lgkmcnt(14)
	v_mfma_f32_32x32x16_bf16 v[48:63], v[136:139], v[104:107], v[48:63]
	v_add_f32_e32 v14, v88, v14
	v_exp_f32_e32 v89, v89
	s_waitcnt lgkmcnt(12)
	v_mfma_f32_32x32x16_bf16 v[64:79], v[136:139], v[156:159], v[64:79]
	v_add_f32_e32 v14, v89, v14
	v_cvt_pk_bf16_f32 v140, v88, v89
	v_exp_f32_e32 v88, v90
	s_waitcnt lgkmcnt(10)
	v_mfma_f32_32x32x16_bf16 v[48:63], v[132:135], v[160:163], v[48:63]
	v_add_f32_e32 v14, v88, v14
	v_exp_f32_e32 v89, v91
	s_waitcnt lgkmcnt(8)
	v_mfma_f32_32x32x16_bf16 v[64:79], v[132:135], v[10:13], v[64:79]
	v_add_f32_e32 v14, v89, v14
	v_cvt_pk_bf16_f32 v141, v88, v89
	v_exp_f32_e32 v10, v92
	s_waitcnt lgkmcnt(6)
	v_mfma_f32_32x32x16_bf16 v[48:63], v[128:131], v[2:5], v[48:63]
	v_add_f32_e32 v2, v10, v14
	s_waitcnt lgkmcnt(4)
	v_mfma_f32_32x32x16_bf16 v[64:79], v[128:131], v[80:83], v[64:79]
	v_exp_f32_e32 v3, v93
	ds_read_b128 v[156:159], v15
	v_add_f32_e32 v2, v3, v2
	v_cvt_pk_bf16_f32 v142, v10, v3
	v_exp_f32_e32 v3, v94
	s_waitcnt lgkmcnt(3)
	v_mfma_f32_32x32x16_bf16 v[48:63], v[124:127], v[6:9], v[48:63]
	v_add_f32_e32 v2, v3, v2
	s_waitcnt lgkmcnt(1)
	v_mfma_f32_32x32x16_bf16 v[64:79], v[124:127], v[84:87], v[64:79]
	v_exp_f32_e32 v4, v95
	ds_read_b128 v[160:163], v15 offset:2048
	v_add_f32_e32 v2, v4, v2
	v_cvt_pk_bf16_f32 v143, v3, v4
	s_add_i32 s48, s51, 0x2000
	s_cmpk_lg_i32 s51, 0x4000
	s_cselect_b32 s74, s48, 0
	s_add_i32 s48, s76, 0x2000
	s_cmpk_lg_i32 s76, 0x6000
	s_waitcnt vmcnt(4) lgkmcnt(0)
	s_barrier
	s_cselect_b32 s75, s48, 0
	s_add_u32 s44, s44, 0x40000
	s_addc_u32 s45, s45, 0
	v_add_f32_e32 v229, v0, v2
	s_cmp_ge_i32 s42, s43
	s_mov_b32 s48, s47
	s_mov_b32 s77, s46
	s_cbranch_scc0 .LBB0_429
	s_add_i32 s43, s42, 1
	s_cmp_lt_i32 s43, s50
	s_mov_b64 s[44:45], -1
	s_cbranch_scc1 .LBB0_432
